# gate-row line touch (1 dword load per wave) at item start for diff/mem items so the epilogue gate loads hit L2/MALL
# baseline (speedup 1.0000x reference)
; DI void diff_core(unsigned char* smem, const u16* qptr, const u16* kbase, const u16* vtbase, int vld,
;                   int ntb, int ntw, int nvalid, int ks0, const float* lut, int qpos, bool active, bool grpB,
;                   f32x16 (&O)[4], float& l_out) {
;     ...
;   asm volatile("s_waitcnt vmcnt(0)" :: "v"(qf[0]), "v"(qf[1]), "v"(qf[2]), "v"(qf[3]) : "memory");
;   dma(0, 0); dma(1 < tlast ? 1 : tlast, 1);
;   if (!grpB) { dma(2 < tlast ? 2 : tlast, 2); asm volatile("s_waitcnt vmcnt(8)" ::: "memory"); }
; __device__ void diff_item(const Params& p, unsigned char* smem, bool sample, int b, int h, int qb, float lam) {
;     ...
;   if (!sample) {
;     const int s = qb * 128 + g * 32 + r;
;     tok = b * SEQ + s;
;     qpos = s - r;
;     ntw = 2 * qb + (g >> 1) + 1;
;     ntb = 2 * qb + 2;
;     nvalid = 64;
;     active = true; valid = true;
;     kbase = p.Kall + (size_t)b * SEQ * 1024 + h * 128;
;     vtbase = p.VTp + (size_t)(b * 1024 + h * 128) * SEQ;
;     vld = SEQ;
;   } else {
;     tok = NPROMPT + b * 16 + (r < 16 ? r : 15);
;     qpos = 1024;
;     ntw = 17; ntb = 17; nvalid = 16;
;     active = (g == 0); valid = (r < 16);
;     kbase = p.Kall + ((size_t)NPROMPT + (size_t)b * SKV) * 1024 + h * 128;
;     vtbase = p.VTs + (size_t)(b * 1024 + h * 128) * SKV;
;     vld = SKV;
;   }
;   const u16* qptr = p.Qb + (size_t)tok * 1024 + h * 128 + c * 64 + hh * 8;
.LBB0_344:
	s_or_b64 exec, exec, s[0:1]
	s_waitcnt lgkmcnt(0)
	s_barrier
	ds_read_b32 v0, v172
	s_movk_i32 s0, 0xff
	s_waitcnt lgkmcnt(0)
	s_barrier
	v_cmp_lt_i32_e32 vcc, s0, v0
	v_readfirstlane_b32 s6, v0
	s_mov_b64 s[0:1], -1
	s_cbranch_vccnz .LBB0_339
	v_mov_b32_e32 v175, v160
	s_ashr_i32 s62, s6, 1
	s_and_b32 s59, s6, 1
	v_readfirstlane_b32 s56, v175
	s_sub_i32 s0, 0x7f, s62
	s_bfe_u32 s39, s56, 0x20006
	s_or_b32 s57, s59, s33
	s_lshl_b32 s1, s0, 7
	s_lshl_b32 s6, s39, 5
	s_lshl_b32 s0, s0, 1
	v_and_b32_e32 v182, 31, v175
	s_ashr_i32 s64, s56, 8
	s_or_b32 s63, s6, s1
	s_or_b32 s58, s0, 1
	s_lshl_b32 s6, s57, 8
	v_or_b32_e32 v0, s34, v182
	s_add_u32 s14, s36, s6
	v_add_u32_e32 v0, s63, v0
	s_addc_u32 s15, s37, 0
	s_lshl_b32 s0, s57, 22
	s_or_b32 s0, s0, s35
	v_ashrrev_i32_e32 v1, 31, v0
	v_readlane_b32 s40, v255, 0
	s_add_u32 s20, s68, s0
	v_lshlrev_b64 v[164:165], 11, v[0:1]
	v_readlane_b32 s52, v255, 12
	v_readlane_b32 s53, v255, 13
	s_addc_u32 s21, s69, 0
	s_lshl_b32 s0, s64, 6
	v_lshl_add_u64 v[0:1], s[52:53], 0, v[164:165]
	v_bfe_u32 v174, v175, 5, 1
	v_lshl_add_u64 v[0:1], v[0:1], 0, s[6:7]
	s_ashr_i32 s1, s0, 31
	v_lshl_add_u64 v[0:1], s[0:1], 1, v[0:1]
	v_lshlrev_b32_e32 v162, 4, v174
	v_lshl_add_u64 v[2:3], v[0:1], 0, v[162:163]
	v_mov_b32_e32 v0, v160
	v_lshlrev_b32_e32 v252, 1, v164
	v_lshl_add_u32 v252, v174, 7, v252
	v_add_u32_e32 v252, s6, v252
	global_load_dword v253, v252, s[80:81]
	global_load_dwordx4 v[128:131], v[2:3], off
	global_load_dwordx4 v[132:135], v[2:3], off offset:32
	global_load_dwordx4 v[136:139], v[2:3], off offset:64
	global_load_dwordx4 v[140:143], v[2:3], off offset:96
	v_readfirstlane_b32 s1, v0
	s_movk_i32 s0, 0xffc0
	s_cmp_eq_u32 s64, 1
	v_mov_b32_e32 v1, s1
	v_bfi_b32 v1, s0, v1, v0
	s_cselect_b64 s[12:13], -1, 0
	s_cmp_lg_u32 s64, 1
	v_ashrrev_i32_e32 v2, 4, v1
	v_lshrrev_b32_e32 v3, 4, v1
	v_lshlrev_b32_e32 v4, 11, v1
	v_add_u32_e32 v1, 0x200, v1
	s_cselect_b64 s[16:17], -1, 0
	s_lshl_b32 s0, s1, 4
	v_xor_b32_e32 v5, v2, v0
	v_lshlrev_b32_e32 v6, 11, v2
	v_xor_b32_e32 v2, v3, v0
	v_ashrrev_i32_e32 v3, 4, v1
	s_and_b32 s0, s0, 0xfffffc00
	v_lshlrev_b32_e32 v7, 4, v5
	v_lshlrev_b32_e32 v2, 3, v2
	v_xor_b32_e32 v5, v3, v0
	s_add_i32 s6, s0, 0
	v_lshlrev_b32_e32 v3, 11, v3
	v_and_b32_e32 v2, 56, v2
	v_lshlrev_b32_e32 v5, 4, v5
	v_and_or_b32 v162, v7, s3, v6
	s_mov_b32 m0, s6
	v_lshlrev_b32_e32 v1, 11, v1
	v_and_or_b32 v4, v4, s22, v2
	v_and_or_b32 v170, v5, s3, v3
	v_and_or_b32 v1, v1, s22, v2
	v_lshlrev_b32_e32 v166, 1, v4
	v_lshlrev_b32_e32 v168, 1, v1
	v_mov_b32_e32 v167, v163
	v_mov_b32_e32 v169, v163
	v_lshl_add_u64 v[2:3], s[20:21], 0, v[166:167]
	v_lshl_add_u64 v[4:5], s[20:21], 0, v[168:169]
	v_lshl_add_u64 v[2:3], v[2:3], 0, s[8:9]
	v_lshl_add_u64 v[4:5], v[4:5], 0, s[8:9]
	v_mov_b32_e32 v171, v163
	v_readlane_b32 s41, v255, 1
	v_readlane_b32 s42, v255, 2
	v_readlane_b32 s43, v255, 3
	v_readlane_b32 s44, v255, 4
	v_readlane_b32 s45, v255, 5
	v_readlane_b32 s46, v255, 6
	v_readlane_b32 s47, v255, 7
	v_readlane_b32 s48, v255, 8
	v_readlane_b32 s49, v255, 9
	v_readlane_b32 s50, v255, 10
	v_readlane_b32 s51, v255, 11
	v_readlane_b32 s54, v255, 14
	v_readlane_b32 s55, v255, 15
	s_nop 0
	s_nop 0
	global_load_lds_dwordx4 v162, s[14:15]
	s_add_i32 m0, s6, 0x2000
	s_nop 0
	global_load_lds_dwordx4 v170, s[14:15]
	s_add_i32 m0, s6, 0x4000
	s_nop 0
	global_load_lds_dwordx4 v166, s[20:21]
	s_add_i32 m0, s6, 0x6000
	s_nop 0
	global_load_lds_dwordx4 v168, s[20:21]
	s_add_i32 m0, s6, 0x8000
	s_add_u32 s0, s14, 0x20000
	s_addc_u32 s1, s15, 0
	global_load_lds_dwordx4 v162, s[0:1]
	s_add_i32 m0, s6, 0xa000
	s_and_b64 vcc, exec, s[12:13]
	global_load_lds_dwordx4 v170, s[0:1]
	s_add_i32 m0, s6, 0xc000
	s_mov_b64 s[0:1], -1
	global_load_lds_dwordx4 v[2:3], off
	s_add_i32 m0, s6, 0xe000
	s_nop 0
	global_load_lds_dwordx4 v[4:5], off
	s_min_u32 s65, s58, 2
	s_add_i32 m0, s6, 0x10000
	s_lshl_b32 s0, s65, 17
	s_add_u32 s0, s14, s0
	s_addc_u32 s1, s15, 0
	v_lshl_add_u64 v[2:3], s[0:1], 0, v[162:163]
	s_lshl_b32 s65, s65, 7
	global_load_lds_dwordx4 v[2:3], off
	s_add_i32 m0, s6, 0x12000
	v_lshl_add_u64 v[2:3], s[0:1], 0, v[170:171]
	s_add_u32 s0, s20, s65
	s_addc_u32 s1, s21, 0
	global_load_lds_dwordx4 v[2:3], off
	v_lshl_add_u64 v[2:3], s[0:1], 0, v[166:167]
	s_add_i32 m0, s6, 0x14000
	s_nop 0
	global_load_lds_dwordx4 v[2:3], off
	v_lshl_add_u64 v[2:3], s[0:1], 0, v[168:169]
	s_add_i32 m0, s6, 0x16000
	s_mov_b64 s[0:1], 0
	global_load_lds_dwordx4 v[2:3], off
	s_waitcnt vmcnt(8)

; template <int NKS>
; DI void flash_core(unsigned char* smem, const u16* qptr, const u16* kbase, int kld, const u16* vtbase, int vld,
;                    int ntb, int ntw, int nvalid, int ks0, const float* lut, int qpos, bool active,
;                    f32x16 (&O)[4], float& m_out, float& l_out) {
;     ...
;   const int krow = tid >> 4, kch = tid & 15;
;   const u16* kg = kbase + (size_t)krow * kld + kch * 8;
;   const int vrow = tid >> 3, vch = tid & 7;
;   const u16* vg = vtbase + (size_t)vrow * vld + vch * 8;
;   const int ksoff = krow * 272 + kch * 16;
;   const int vsoff = 17408 + vrow * 144 + vch * 16;
;   u32x4 kr0, kr1, vr0, vr1;
;   kr0 = *reinterpret_cast<const u32x4*>(kg);
;   kr1 = *reinterpret_cast<const u32x4*>(kg + (size_t)32 * kld);
;   vr0 = *reinterpret_cast<const u32x4*>(vg);
;   vr1 = *reinterpret_cast<const u32x4*>(vg + (size_t)64 * vld);
;   *reinterpret_cast<u32x4*>(smem + ksoff) = kr0;
;   *reinterpret_cast<u32x4*>(smem + ksoff + 32 * 272) = kr1;
;   *reinterpret_cast<u32x4*>(smem + vsoff) = vr0;
;   *reinterpret_cast<u32x4*>(smem + vsoff + 64 * 144) = vr1;
;   __syncthreads();
;   for (int t = 0; t < ntb; ++t) {
;     const unsigned char* cur = smem + (t & 1) * TILEB;
;     unsigned char* nxt = smem + ((t + 1) & 1) * TILEB;
;     const bool more = (t + 1 < ntb);
;     if (more) {
;       kr0 = *reinterpret_cast<const u32x4*>(kg + (size_t)(64 * (t + 1)) * kld);
;       kr1 = *reinterpret_cast<const u32x4*>(kg + (size_t)(64 * (t + 1) + 32) * kld);
;       vr0 = *reinterpret_cast<const u32x4*>(vg + 64 * (t + 1));
;       vr1 = *reinterpret_cast<const u32x4*>(vg + (size_t)64 * vld + 64 * (t + 1));
;     }
;     if (active && t < ntw) {
;       f32x16 S[2];
; #pragma unroll
;       for (int kb = 0; kb < 2; ++kb)
; #pragma unroll
;         for (int e = 0; e < 16; ++e) S[kb][e] = 0.f;
;       const unsigned char* kb0 = cur + r * 272 + (ks0 * 16 + hh * 8) * 2;
; #pragma unroll
;       for (int s = 0; s < NKS; ++s)
; __device__ void mem_item(const Params& p, unsigned char* smem, bool sample, int b, int h, int qblk) {
;     ...
;   } else {
;     tok = NPROMPT + b * 16 + (r < 16 ? r : 15);
;     mb = 2 + b;
;     active = (w == 0); valid = (r < 16);
;   }
;   const u16* qptr = p.MQb + (size_t)tok * 512 + h * 128 + hh * 8;
;   const u16* kbase = p.MKall + (size_t)mb * 256 * 512 + h * 128;
;   const u16* vtbase = p.MVTall + (size_t)(mb * 4 + h) * 128 * 256;
.LBB0_516:
	s_and_b64 vcc, exec, s[8:9]
	s_cbranch_vccz .LBB0_519
	s_add_i32 s8, s2, 0xfffffd00
	s_lshr_b32 s10, s8, 2
	v_mov_b32_e32 v28, v160
	s_lshl_b32 s8, s10, 4
	s_and_b32 s38, s2, 3
	s_add_i32 s12, s8, 0x8000
	v_readfirstlane_b32 s11, v28
	v_and_b32_e32 v0, 31, v28
	s_add_i32 s10, s10, 2
	v_cmp_gt_u32_e64 s[8:9], 16, v0
	s_cmp_lt_u32 s11, 64
	s_cselect_b64 s[16:17], -1, 0
	v_cndmask_b32_e64 v0, 15, v0, s[8:9]
	s_cmp_gt_u32 s11, 63
	s_mov_b32 s11, s23
	v_add_u32_e32 v164, s12, v0
	s_cselect_b64 s[12:13], -1, 0
	s_lshl_b32 s22, s38, 8
	s_lshl_b64 s[58:59], s[10:11], 18
	s_add_u32 s11, s82, s58
	s_addc_u32 s39, s83, s59
	v_mov_b32_e32 v30, v160
	v_lshlrev_b64 v[0:1], 10, v[164:165]
	s_add_u32 s58, s11, s22
	v_lshl_add_u64 v[0:1], s[78:79], 0, v[0:1]
	v_ashrrev_i32_e32 v18, 4, v30
	s_addc_u32 s59, s39, 0
	s_lshl_b32 s10, s10, 2
	v_ashrrev_i32_e32 v19, 31, v18
	v_lshl_add_u64 v[16:17], v[0:1], 0, s[22:23]
	s_or_b32 s22, s10, s38
	v_lshlrev_b64 v[0:1], 10, v[18:19]
	v_lshlrev_b32_e32 v2, 4, v30
	s_lshl_b64 s[10:11], s[22:23], 16
	v_readlane_b32 s60, v255, 50
	v_lshl_add_u64 v[0:1], s[58:59], 0, v[0:1]
	v_and_b32_e32 v20, 0xf0, v2
	v_mov_b32_e32 v21, v165
	v_ashrrev_i32_e32 v22, 3, v30
	v_readlane_b32 s61, v255, 51
	s_add_u32 s10, s60, s10
	v_lshl_add_u64 v[144:145], v[0:1], 0, v[20:21]
	v_ashrrev_i32_e32 v23, 31, v22
	s_addc_u32 s11, s61, s11
	v_lshlrev_b64 v[0:1], 9, v[22:23]
	v_add_co_u32_e32 v4, vcc, s34, v144
	v_lshl_add_u64 v[0:1], s[10:11], 0, v[0:1]
	v_and_b32_e32 v24, 0x70, v2
	v_mov_b32_e32 v25, v165
	v_addc_co_u32_e32 v5, vcc, 0, v145, vcc
	v_lshl_add_u64 v[146:147], v[0:1], 0, v[24:25]
	v_bfe_u32 v196, v160, 5, 1
	v_lshlrev_b32_e32 v196, 7, v196
	v_lshl_add_u32 v196, v164, 12, v196
	v_lshl_add_u32 v196, s38, 8, v196
	global_load_dword v195, v196, s[80:81] offset:3072
	global_load_dwordx4 v[0:3], v[144:145], off
	s_nop 0
	global_load_dwordx4 v[4:7], v[4:5], off
	s_nop 0
	global_load_dwordx4 v[8:11], v[146:147], off
	v_add_co_u32_e32 v26, vcc, s34, v146
	v_bfe_u32 v148, v28, 5, 1
	s_nop 0
	v_addc_co_u32_e32 v27, vcc, 0, v147, vcc
	global_load_dwordx4 v[12:15], v[26:27], off
	v_mov_b32_e32 v29, v165
	v_lshlrev_b32_e32 v28, 4, v148
	v_lshl_add_u64 v[16:17], v[16:17], 0, v[28:29]
	global_load_dwordx4 v[124:127], v[16:17], off
	global_load_dwordx4 v[120:123], v[16:17], off offset:32
	global_load_dwordx4 v[116:119], v[16:17], off offset:64
	global_load_dwordx4 v[112:115], v[16:17], off offset:96
	global_load_dwordx4 v[108:111], v[16:17], off offset:128
	global_load_dwordx4 v[104:107], v[16:17], off offset:160
	global_load_dwordx4 v[100:103], v[16:17], off offset:192
	global_load_dwordx4 v[96:99], v[16:17], off offset:224
	v_add_co_u32_e32 v16, vcc, 0x10000, v144
	v_mad_u64_u32 v[18:19], s[10:11], v18, s26, v[20:21]
	s_nop 0
	v_addc_co_u32_e32 v17, vcc, 0, v145, vcc
	v_mad_u64_u32 v[20:21], s[10:11], v22, s27, v[24:25]
	v_add_u32_e32 v153, 0, v18
	v_add_co_u32_e32 v18, vcc, 0x18000, v144
	v_add_u32_e32 v152, 0, v20
	s_nop 0
	v_addc_co_u32_e32 v19, vcc, 0, v145, vcc
	s_and_b64 vcc, exec, s[16:17]
	s_waitcnt vmcnt(11)
	ds_write_b128 v153, v[0:3]
	s_waitcnt vmcnt(10)
	ds_write_b128 v153, v[4:7] offset:8704
	s_waitcnt vmcnt(9)
	ds_write_b128 v152, v[8:11] offset:17408
	s_waitcnt vmcnt(8)
	ds_write_b128 v152, v[12:15] offset:26624
	s_waitcnt lgkmcnt(0)
	s_barrier
	global_load_dwordx4 v[128:131], v[16:17], off
	global_load_dwordx4 v[132:135], v[18:19], off
	global_load_dwordx4 v[136:139], v[146:147], off offset:128
	global_load_dwordx4 v[140:143], v[26:27], off offset:128
	v_and_b32_e32 v0, 31, v30
	v_lshrrev_b32_e32 v2, 1, v30
	v_mul_u32_u24_e32 v1, 0x110, v0
	v_and_b32_e32 v2, 16, v2
	v_add3_u32 v151, 0, v1, v2
	v_lshlrev_b32_e32 v0, 7, v0
	v_sub_u32_e32 v149, v151, v0
	s_cbranch_vccz .LBB0_582
	ds_read_b128 v[0:3], v151
	ds_read_b128 v[4:7], v151 offset:32
	s_mov_b32 s10, 0xf149f2ca
	s_waitcnt vmcnt(11) lgkmcnt(1)
	v_mfma_f32_32x32x16_bf16 v[80:95], v[0:3], v[124:127], 0
	ds_read_b128 v[0:3], v151 offset:8704
	ds_read_b128 v[8:11], v151 offset:8736
	s_waitcnt vmcnt(10) lgkmcnt(2)
	v_mfma_f32_32x32x16_bf16 v[80:95], v[4:7], v[120:123], v[80:95]
	s_waitcnt lgkmcnt(1)
	v_mfma_f32_32x32x16_bf16 v[64:79], v[0:3], v[124:127], 0
	ds_read_b128 v[0:3], v151 offset:64
	ds_read_b128 v[4:7], v151 offset:96
	s_waitcnt vmcnt(9) lgkmcnt(1)
	v_mfma_f32_32x32x16_bf16 v[80:95], v[0:3], v[116:119], v[80:95]
	v_mfma_f32_32x32x16_bf16 v[64:79], v[8:11], v[120:123], v[64:79]
	ds_read_b128 v[0:3], v151 offset:8768
	ds_read_b128 v[8:11], v151 offset:8800
	s_waitcnt vmcnt(8) lgkmcnt(2)
	v_mfma_f32_32x32x16_bf16 v[80:95], v[4:7], v[112:115], v[80:95]
	s_waitcnt lgkmcnt(1)
	v_mfma_f32_32x32x16_bf16 v[64:79], v[0:3], v[116:119], v[64:79]
	ds_read_b128 v[0:3], v151 offset:128
	ds_read_b128 v[4:7], v151 offset:160
	s_waitcnt vmcnt(7) lgkmcnt(1)
	v_mfma_f32_32x32x16_bf16 v[80:95], v[0:3], v[108:111], v[80:95]
	v_mfma_f32_32x32x16_bf16 v[64:79], v[8:11], v[112:115], v[64:79]
	ds_read_b128 v[0:3], v151 offset:8832
	ds_read_b128 v[8:11], v151 offset:8864
	s_waitcnt vmcnt(6) lgkmcnt(2)
	v_mfma_f32_32x32x16_bf16 v[80:95], v[4:7], v[104:107], v[80:95]
	s_waitcnt lgkmcnt(1)
	v_mfma_f32_32x32x16_bf16 v[64:79], v[0:3], v[108:111], v[64:79]
	ds_read_b128 v[0:3], v151 offset:192
	ds_read_b128 v[4:7], v151 offset:224
	s_waitcnt vmcnt(5) lgkmcnt(1)
	v_mfma_f32_32x32x16_bf16 v[80:95], v[0:3], v[100:103], v[80:95]
	v_mfma_f32_32x32x16_bf16 v[64:79], v[8:11], v[104:107], v[64:79]
	s_waitcnt vmcnt(4) lgkmcnt(0)
	v_mfma_f32_32x32x16_bf16 v[80:95], v[4:7], v[96:99], v[80:95]
	ds_read_b128 v[0:3], v151 offset:8896
	ds_read_b128 v[4:7], v151 offset:8928
	ds_read_b128 v[16:19], v149 offset:17408
	s_waitcnt lgkmcnt(2)
; #define MFMA(a, b, c) __builtin_amdgcn_mfma_f32_32x32x16_bf16((a), (b), (c), 0, 0, 0)
; template <int NKS>
; DI void flash_core(unsigned char* smem, const u16* qptr, const u16* kbase, int kld, const u16* vtbase, int vld,
;                    int ntb, int ntw, int nvalid, int ks0, const float* lut, int qpos, bool active,
;                    f32x16 (&O)[4], float& m_out, float& l_out) {
;     ...
;       float mx = m;
; #pragma unroll
;       for (int kb = 0; kb < 2; ++kb)
; #pragma unroll
;         for (int i = 0; i < 16; ++i) mx = fmaxf(mx, S[kb][i]);
;       mx = fmaxf(mx, __shfl_xor(mx, 32));
;       const float alpha = __builtin_amdgcn_exp2f(m - mx);
;       m = mx;
;       float ps = 0.f;
; #pragma unroll
;       for (int kb = 0; kb < 2; ++kb)
; #pragma unroll
;         for (int i = 0; i < 16; ++i) {
;           const float pv = __builtin_amdgcn_exp2f(S[kb][i] - mx);
;           S[kb][i] = pv;
;           ps += pv;
;         }
;       l = l * alpha + ps;
; #pragma unroll
;       for (int tt = 0; tt < 4; ++tt)
; #pragma unroll
;         for (int e = 0; e < 16; ++e) O[tt][e] *= alpha;
;       const unsigned char* vb0 = cur + 17408 + r * 144 + hh * 16;
; #pragma unroll
;       for (int kb = 0; kb < 2; ++kb)
; #pragma unroll
;         for (int s2 = 0; s2 < 2; ++s2) {
;           u32x4 pk;
;           pk.x = pack2(S[kb][8 * s2 + 0], S[kb][8 * s2 + 1]);
;           pk.y = pack2(S[kb][8 * s2 + 2], S[kb][8 * s2 + 3]);
;           pk.z = pack2(S[kb][8 * s2 + 4], S[kb][8 * s2 + 5]);
;           pk.w = pack2(S[kb][8 * s2 + 6], S[kb][8 * s2 + 7]);
;           const bf16x8 pf = __builtin_bit_cast(bf16x8, pk);
; #pragma unroll
;           for (int tt = 0; tt < 4; ++tt) {
;             const bf16x8 vf = *reinterpret_cast<const bf16x8*>(vb0 + tt * 32 * 144 + (kb * 32 + s2 * 16) * 2);
;             O[tt] = MFMA(vf, pf, O[tt]);
;           }
;         }
	v_mfma_f32_32x32x16_bf16 v[64:79], v[0:3], v[100:103], v[64:79]
	s_nop 6
	v_max3_f32 v8, v80, s10, v81
	v_max3_f32 v0, v8, v82, v83
	v_max3_f32 v0, v0, v84, v85
	v_max3_f32 v0, v0, v86, v87
	v_max3_f32 v0, v0, v88, v89
	v_max3_f32 v0, v0, v90, v91
	v_max3_f32 v0, v0, v92, v93
	s_waitcnt lgkmcnt(1)
	v_mfma_f32_32x32x16_bf16 v[64:79], v[4:7], v[96:99], v[64:79]
	v_max3_f32 v0, v0, v94, v95
	v_and_b32_e32 v2, 64, v161
	v_xor_b32_e32 v1, 32, v161
	v_add_u32_e32 v2, 64, v2
	v_cmp_lt_i32_e32 vcc, v1, v2
	s_nop 6
	v_max3_f32 v0, v0, v64, v65
	v_max3_f32 v0, v0, v66, v67
	v_max3_f32 v0, v0, v68, v69
	v_max3_f32 v0, v0, v70, v71
	v_max3_f32 v0, v0, v72, v73
	v_max3_f32 v0, v0, v74, v75
	v_max3_f32 v0, v0, v76, v77
	v_cndmask_b32_e32 v1, v161, v1, vcc
	v_max3_f32 v0, v0, v78, v79
	v_lshlrev_b32_e32 v1, 2, v1
	ds_bpermute_b32 v1, v1, v0
	s_waitcnt lgkmcnt(0)
	v_max_f32_e32 v1, v1, v1
	v_max_f32_e32 v154, v0, v1
	v_sub_f32_e32 v1, v81, v154
	v_exp_f32_e32 v25, v1
	v_sub_f32_e32 v1, v82, v154
	v_exp_f32_e32 v26, v1
	v_sub_f32_e32 v1, v83, v154
	v_sub_f32_e32 v0, v80, v154
	v_exp_f32_e32 v27, v1
	v_sub_f32_e32 v1, v84, v154
	v_exp_f32_e32 v20, v0
	v_sub_f32_e32 v0, 0xf149f2ca, v154
	v_exp_f32_e32 v150, v1
	v_sub_f32_e32 v1, v85, v154
	v_exp_f32_e32 v155, v1
	v_sub_f32_e32 v1, v86, v154
	v_exp_f32_e32 v188, v0
	v_sub_f32_e32 v0, v87, v154
	v_exp_f32_e32 v189, v1
	v_exp_f32_e32 v190, v0
	v_mul_f32_e32 v0, 0, v188
	v_add_f32_e32 v24, 0, v20
	v_mov_b32_e32 v1, v0
	v_mov_b32_e32 v2, v0
	v_mov_b32_e32 v3, v0
	v_mov_b32_e32 v4, v0
	v_mov_b32_e32 v5, v0
	v_mov_b32_e32 v6, v0
	v_mov_b32_e32 v7, v0
	v_mov_b32_e32 v8, v0
	v_mov_b32_e32 v9, v0
	v_mov_b32_e32 v10, v0
	v_mov_b32_e32 v11, v0
	v_mov_b32_e32 v12, v0
	v_mov_b32_e32 v13, v0
	v_mov_b32_e32 v14, v0
	v_mov_b32_e32 v15, v0
	v_cvt_pk_bf16_f32 v80, v20, v25
	v_cvt_pk_bf16_f32 v81, v26, v27
	v_cvt_pk_bf16_f32 v82, v150, v155
	v_cvt_pk_bf16_f32 v83, v189, v190
	ds_read_b128 v[84:87], v149 offset:17440
	ds_read_b128 v[20:23], v149 offset:22016
	v_mfma_f32_32x32x16_bf16 v[48:63], v[16:19], v[80:83], v[0:15]
	v_add_f32_e32 v16, v25, v24
	v_add_f32_e32 v16, v26, v16
	v_add_f32_e32 v191, v27, v16
	v_sub_f32_e32 v16, v88, v154
	v_exp_f32_e32 v194, v16
	v_sub_f32_e32 v16, v89, v154
	ds_read_b128 v[156:159], v149 offset:26624
	ds_read_b128 v[180:183], v149 offset:22048
	v_exp_f32_e32 v198, v16
	v_sub_f32_e32 v16, v90, v154
	v_sub_f32_e32 v201, v91, v154
	ds_read_b128 v[88:91], v149 offset:31232
	ds_read_b128 v[184:187], v149 offset:26656
	s_waitcnt lgkmcnt(4)
	v_mfma_f32_32x32x16_bf16 v[32:47], v[20:23], v[80:83], v[0:15]
	v_exp_f32_e32 v200, v16
	v_sub_f32_e32 v92, v92, v154
	v_sub_f32_e32 v93, v93, v154
	v_sub_f32_e32 v94, v94, v154
	v_exp_f32_e32 v201, v201
	v_exp_f32_e32 v92, v92
	v_exp_f32_e32 v93, v93
	s_waitcnt lgkmcnt(3)
	v_mfma_f32_32x32x16_bf16 v[16:31], v[156:159], v[80:83], v[0:15]
	v_exp_f32_e32 v94, v94
	v_sub_f32_e32 v64, v64, v154
	ds_read_b128 v[156:159], v149 offset:31264
	v_sub_f32_e32 v78, v78, v154
	s_waitcnt lgkmcnt(2)
	v_mfma_f32_32x32x16_bf16 v[0:15], v[88:91], v[80:83], v[0:15]
	v_sub_f32_e32 v80, v95, v154
	v_exp_f32_e32 v95, v80
	v_cvt_pk_bf16_f32 v80, v194, v198
	v_cvt_pk_bf16_f32 v81, v200, v201
	v_cvt_pk_bf16_f32 v82, v92, v93
	v_cvt_pk_bf16_f32 v83, v94, v95
	s_nop 1
	v_mfma_f32_32x32x16_bf16 v[48:63], v[84:87], v[80:83], v[48:63]
	v_add_f32_e32 v84, v150, v191
	v_exp_f32_e32 v150, v64
	v_sub_f32_e32 v64, v65, v154
	v_add_f32_e32 v84, v155, v84
	v_exp_f32_e32 v155, v64
	v_sub_f32_e32 v64, v66, v154
	v_add_f32_e32 v84, v189, v84
	v_mfma_f32_32x32x16_bf16 v[32:47], v[180:183], v[80:83], v[32:47]
	v_exp_f32_e32 v180, v64
	v_sub_f32_e32 v64, v67, v154
	v_exp_f32_e32 v181, v64
	v_sub_f32_e32 v64, v68, v154
	v_exp_f32_e32 v182, v64
	v_sub_f32_e32 v64, v69, v154
	v_exp_f32_e32 v183, v64
	v_sub_f32_e32 v64, v70, v154
	s_waitcnt lgkmcnt(1)
	v_mfma_f32_32x32x16_bf16 v[16:31], v[184:187], v[80:83], v[16:31]
	v_exp_f32_e32 v184, v64
	ds_read_b128 v[64:67], v149 offset:17472
	v_sub_f32_e32 v68, v71, v154
	v_add_f32_e32 v84, v190, v84
	v_add_f32_e32 v88, v194, v84
	v_cvt_pk_bf16_f32 v69, v180, v181
	v_cvt_pk_bf16_f32 v70, v182, v183
	s_waitcnt lgkmcnt(1)
	v_mfma_f32_32x32x16_bf16 v[0:15], v[156:159], v[80:83], v[0:15]
	v_exp_f32_e32 v156, v68
	v_cvt_pk_bf16_f32 v68, v150, v155
	ds_read_b128 v[80:83], v149 offset:22080
	ds_read_b128 v[84:87], v149 offset:17504
	v_sub_f32_e32 v186, v75, v154
	v_cvt_pk_bf16_f32 v71, v184, v156
	v_exp_f32_e32 v186, v186
	s_waitcnt lgkmcnt(2)
	v_mfma_f32_32x32x16_bf16 v[48:63], v[64:67], v[68:71], v[48:63]
	v_add_f32_e32 v64, v198, v88
	v_add_f32_e32 v64, v200, v64
	v_add_f32_e32 v157, v201, v64
	v_sub_f32_e32 v64, v72, v154
	v_sub_f32_e32 v72, v73, v154
	v_exp_f32_e32 v159, v72
	v_sub_f32_e32 v72, v74, v154
	v_exp_f32_e32 v158, v64
	ds_read_b128 v[64:67], v149 offset:26688
	ds_read_b128 v[88:91], v149 offset:22112
	s_waitcnt lgkmcnt(3)
	v_mfma_f32_32x32x16_bf16 v[32:47], v[80:83], v[68:71], v[32:47]
	v_exp_f32_e32 v185, v72
	ds_read_b128 v[72:75], v149 offset:31296
	ds_read_b128 v[80:83], v149 offset:26720
	s_waitcnt lgkmcnt(1)
	v_mfma_f32_32x32x16_bf16 v[0:15], v[72:75], v[68:71], v[0:15]
	v_add_f32_e32 v74, v92, v157
	v_add_f32_e32 v74, v93, v74
	v_add_f32_e32 v74, v94, v74
	v_add_f32_e32 v74, v95, v74
	v_add_f32_e32 v74, v150, v74
	v_add_f32_e32 v74, v155, v74
	v_add_f32_e32 v74, v180, v74
	v_mfma_f32_32x32x16_bf16 v[16:31], v[64:67], v[68:71], v[16:31]
	v_sub_f32_e32 v64, v76, v154
	v_exp_f32_e32 v76, v64
	v_sub_f32_e32 v64, v77, v154
	v_exp_f32_e32 v77, v64
	ds_read_b128 v[64:67], v149 offset:31328
	v_sub_f32_e32 v68, v79, v154
	v_add_f32_e32 v74, v181, v74
	v_exp_f32_e32 v72, v78
	v_exp_f32_e32 v73, v68
	v_add_f32_e32 v74, v182, v74
	v_add_f32_e32 v74, v183, v74
	v_add_f32_e32 v74, v184, v74
	v_add_f32_e32 v74, v156, v74
	v_cvt_pk_bf16_f32 v68, v158, v159
	v_cvt_pk_bf16_f32 v69, v185, v186
	v_cvt_pk_bf16_f32 v70, v76, v77
	v_cvt_pk_bf16_f32 v71, v72, v73
	v_add_f32_e32 v74, v158, v74
	v_add_f32_e32 v74, v159, v74
	v_mfma_f32_32x32x16_bf16 v[48:63], v[84:87], v[68:71], v[48:63]
	v_add_f32_e32 v74, v185, v74
	v_add_f32_e32 v74, v186, v74
	v_add_f32_e32 v74, v76, v74
	v_add_f32_e32 v74, v77, v74
	v_add_f32_e32 v72, v72, v74
	v_add_f32_e32 v150, v73, v72
	v_fmac_f32_e32 v150, 0, v188
	v_mfma_f32_32x32x16_bf16 v[32:47], v[88:91], v[68:71], v[32:47]
	s_waitcnt lgkmcnt(1)
	v_mfma_f32_32x32x16_bf16 v[16:31], v[80:83], v[68:71], v[16:31]
	s_waitcnt lgkmcnt(0)
	v_mfma_f32_32x32x16_bf16 v[0:15], v[64:67], v[68:71], v[0:15]
	s_branch .LBB0_583

; template <int NKS>
; DI void flash_core(unsigned char* smem, const u16* qptr, const u16* kbase, int kld, const u16* vtbase, int vld,
;                    int ntb, int ntw, int nvalid, int ks0, const float* lut, int qpos, bool active,
;                    f32x16 (&O)[4], float& m_out, float& l_out) {
;     ...
; #pragma unroll
;   for (int s = 0; s < NKS; ++s) qf[s] = *reinterpret_cast<const bf16x8*>(qptr + s * 16);
; #pragma unroll
;   for (int t = 0; t < 4; ++t)
; #pragma unroll
;     for (int e = 0; e < 16; ++e) O[t][e] = 0.f;
;   float m = -1e30f, l = 0.f;
;   const int krow = tid >> 4, kch = tid & 15;
;   const u16* kg = kbase + (size_t)krow * kld + kch * 8;
;   const int vrow = tid >> 3, vch = tid & 7;
;   const u16* vg = vtbase + (size_t)vrow * vld + vch * 8;
;   const int ksoff = krow * 272 + kch * 16;
;   const int vsoff = 17408 + vrow * 144 + vch * 16;
;   u32x4 kr0, kr1, vr0, vr1;
;   kr0 = *reinterpret_cast<const u32x4*>(kg);
;   kr1 = *reinterpret_cast<const u32x4*>(kg + (size_t)32 * kld);
;   vr0 = *reinterpret_cast<const u32x4*>(vg);
;   vr1 = *reinterpret_cast<const u32x4*>(vg + (size_t)64 * vld);
;   *reinterpret_cast<u32x4*>(smem + ksoff) = kr0;
;   *reinterpret_cast<u32x4*>(smem + ksoff + 32 * 272) = kr1;
;   *reinterpret_cast<u32x4*>(smem + vsoff) = vr0;
;   *reinterpret_cast<u32x4*>(smem + vsoff + 64 * 144) = vr1;
;   __syncthreads();
; __device__ void mem_item(const Params& p, unsigned char* smem, bool sample, int b, int h, int qblk) {
;     ...
;   if (!sample) {
;     tok = qblk * 256 + w * 32 + r;
;     mb = tok >> 14;
;     active = true; valid = true;
;   } else {
;     tok = NPROMPT + b * 16 + (r < 16 ? r : 15);
;     mb = 2 + b;
;     active = (w == 0); valid = (r < 16);
;   }
;   const u16* qptr = p.MQb + (size_t)tok * 512 + h * 128 + hh * 8;
;   const u16* kbase = p.MKall + (size_t)mb * 256 * 512 + h * 128;
;   const u16* vtbase = p.MVTall + (size_t)(mb * 4 + h) * 128 * 256;
;   f32x16 O[4];
;   float m, l;
;   flash_core<8>(smem, qptr, kbase, 512, vtbase, 256, 4, 4, 64, 0, nullptr, 0, active, O, m, l);
.LBB0_521:
	v_mov_b32_e32 v0, v160
	s_lshl_b32 s9, s2, 6
	v_readfirstlane_b32 s8, v0
	s_ashr_i32 s8, s8, 1
	s_and_b32 s9, s9, 0xff00
	s_andn2_b32 s8, s8, 31
	s_add_i32 s8, s9, s8
	s_addk_i32 s8, 0xc000
	s_ashr_i32 s10, s8, 14
	s_and_b32 s13, s2, 3
	s_ashr_i32 s11, s10, 31
	v_and_or_b32 v140, v0, 31, s8
	s_lshl_b32 s12, s13, 7
	s_lshl_b32 s22, s13, 8
	s_lshl_b64 s[8:9], s[10:11], 18
	s_add_u32 s11, s82, s8
	s_addc_u32 s17, s83, s9
	s_add_u32 s16, s11, s22
	s_addc_u32 s17, s17, 0
	s_lshl_b32 s10, s10, 2
	v_ashrrev_i32_e32 v141, 31, v140
	s_or_b32 s10, s10, s13
	v_mov_b32_e32 v30, v160
	v_bfe_u32 v154, v0, 5, 1
	v_lshlrev_b64 v[0:1], 10, v[140:141]
	s_ashr_i32 s11, s10, 31
	v_lshl_add_u64 v[0:1], s[78:79], 0, v[0:1]
	v_ashrrev_i32_e32 v20, 4, v30
	s_lshl_b64 s[10:11], s[10:11], 16
	v_readlane_b32 s38, v255, 50
	v_ashrrev_i32_e32 v21, 31, v20
	v_ashrrev_i32_e32 v24, 3, v30
	v_lshl_add_u64 v[0:1], v[0:1], 0, s[22:23]
	v_lshlrev_b32_e32 v164, 4, v154
	v_readlane_b32 s39, v255, 51
	s_add_u32 s38, s38, s10
	v_lshlrev_b64 v[22:23], 10, v[20:21]
	v_lshlrev_b32_e32 v4, 4, v30
	v_ashrrev_i32_e32 v25, 31, v24
	v_lshl_add_u64 v[18:19], v[0:1], 0, v[164:165]
	s_addc_u32 s39, s39, s11
	v_lshl_add_u64 v[0:1], s[16:17], 0, v[22:23]
	v_and_b32_e32 v164, 0xf0, v4
	v_lshlrev_b64 v[26:27], 9, v[24:25]
	v_lshl_add_u64 v[0:1], v[0:1], 0, v[164:165]
	v_lshl_add_u64 v[2:3], s[38:39], 0, v[26:27]
	v_and_b32_e32 v28, 0x70, v4
	v_mov_b32_e32 v29, v165
	v_lshl_add_u64 v[14:15], v[2:3], 0, v[28:29]
	v_lshlrev_b32_e32 v196, 12, v140
	v_lshl_add_u32 v196, v154, 7, v196
	v_add_u32_e32 v196, s22, v196
	global_load_dword v195, v196, s[80:81] offset:3072
	global_load_dwordx4 v[2:5], v[0:1], off
	v_add_co_u32_e32 v0, vcc, s34, v0
	v_and_b32_e32 v21, 64, v161
	s_nop 0
	v_addc_co_u32_e32 v1, vcc, 0, v1, vcc
	global_load_dwordx4 v[6:9], v[0:1], off
	global_load_dwordx4 v[10:13], v[14:15], off
	v_add_co_u32_e32 v0, vcc, s34, v14
	v_add_u32_e32 v21, 64, v21
	s_nop 0
	v_addc_co_u32_e32 v1, vcc, 0, v15, vcc
	global_load_dwordx4 v[14:17], v[0:1], off
	global_load_dwordx4 v[124:127], v[18:19], off
	global_load_dwordx4 v[120:123], v[18:19], off offset:32
	global_load_dwordx4 v[116:119], v[18:19], off offset:64
	global_load_dwordx4 v[112:115], v[18:19], off offset:96
	global_load_dwordx4 v[108:111], v[18:19], off offset:128
	global_load_dwordx4 v[104:107], v[18:19], off offset:160
	global_load_dwordx4 v[100:103], v[18:19], off offset:192
	global_load_dwordx4 v[96:99], v[18:19], off offset:224
	v_xor_b32_e32 v1, 32, v161
	v_lshl_add_u64 v[18:19], s[8:9], 0, v[22:23]
	v_cmp_lt_i32_e32 vcc, v1, v21
	v_or3_b32 v18, v18, s22, v164
	v_mad_u64_u32 v[142:143], s[38:39], v24, s27, v[28:29]
	v_cndmask_b32_e32 v1, v161, v1, vcc
	v_mad_u64_u32 v[144:145], s[8:9], v20, s26, v[164:165]
	v_lshl_add_u64 v[146:147], s[14:15], 0, v[18:19]
	v_lshl_add_u64 v[18:19], s[10:11], 0, v[26:27]
	v_mov_b32_e32 v128, 0
	v_and_b32_e32 v156, 31, v30
	v_lshrrev_b32_e32 v25, 1, v30
	v_lshlrev_b32_e32 v155, 2, v1
	v_add_u32_e32 v1, 0, v142
	v_add_u32_e32 v20, 0, v144
	v_or_b32_e32 v18, v18, v28
	s_mov_b32 s16, 0
	v_mov_b32_e32 v136, 0xf149f2ca
	v_mov_b32_e32 v0, 0
	v_mul_u32_u24_e32 v157, 0x110, v156
	v_and_b32_e32 v158, 16, v25
	v_mul_u32_u24_e32 v159, 0x90, v156
	v_lshl_add_u64 v[148:149], s[20:21], 0, v[18:19]
	v_mov_b32_e32 v18, v128
	v_mov_b32_e32 v19, v128
	v_mov_b32_e32 v21, v128
	v_mov_b32_e32 v22, v128
	v_mov_b32_e32 v23, v128
	v_mov_b32_e32 v24, v128
	v_mov_b32_e32 v25, v128
	v_mov_b32_e32 v26, v128
	v_mov_b32_e32 v27, v128
	v_mov_b32_e32 v28, v128
	v_mov_b32_e32 v29, v128
	s_waitcnt vmcnt(11)
	ds_write_b128 v20, v[2:5]
	s_waitcnt vmcnt(10)
	ds_write_b128 v20, v[6:9] offset:8704
	s_waitcnt vmcnt(9)
	ds_write_b128 v1, v[10:13] offset:17408
	s_waitcnt vmcnt(8)
	ds_write_b128 v1, v[14:17] offset:26624
	v_mov_b32_e32 v1, v128
	v_mov_b32_e32 v2, v128
	v_mov_b32_e32 v3, v128
	v_mov_b32_e32 v4, v128
	v_mov_b32_e32 v5, v128
	v_mov_b32_e32 v6, v128
	v_mov_b32_e32 v7, v128
	v_mov_b32_e32 v8, v128
	v_mov_b32_e32 v9, v128
	v_mov_b32_e32 v10, v128
	v_mov_b32_e32 v11, v128
	v_mov_b32_e32 v12, v128
	v_mov_b32_e32 v13, v128
	v_mov_b32_e32 v14, v128
	v_mov_b32_e32 v15, v128
	v_mov_b32_e32 v16, 0
	v_mov_b32_e32 v17, v128
	v_mov_b32_e32 v20, v128
	v_mov_b32_e32 v30, v128
	v_mov_b32_e32 v31, v128
	v_mov_b32_e32 v32, 0
	v_mov_b32_e32 v33, v128
	v_mov_b32_e32 v34, v128
	v_mov_b32_e32 v35, v128
	v_mov_b32_e32 v36, v128
	v_mov_b32_e32 v37, v128
	v_mov_b32_e32 v38, v128
	v_mov_b32_e32 v39, v128
	v_mov_b32_e32 v40, v128
	v_mov_b32_e32 v41, v128
	v_mov_b32_e32 v42, v128
	v_mov_b32_e32 v43, v128
	v_mov_b32_e32 v44, v128
	v_mov_b32_e32 v45, v128
	v_mov_b32_e32 v46, v128
	v_mov_b32_e32 v47, v128
	v_mov_b32_e32 v48, 0
	v_mov_b32_e32 v49, v128
	v_mov_b32_e32 v50, v128
	v_mov_b32_e32 v51, v128
	v_mov_b32_e32 v52, v128
	v_mov_b32_e32 v53, v128
	v_mov_b32_e32 v54, v128
	v_mov_b32_e32 v55, v128
	v_mov_b32_e32 v56, v128
	v_mov_b32_e32 v57, v128
	v_mov_b32_e32 v58, v128
	v_mov_b32_e32 v59, v128
	v_mov_b32_e32 v60, v128
	v_mov_b32_e32 v61, v128
	v_mov_b32_e32 v62, v128
	v_mov_b32_e32 v63, v128
	s_waitcnt lgkmcnt(0)
	s_barrier

; #define D_BAR do { asm volatile("" ::: "memory"); __builtin_amdgcn_s_barrier(); asm volatile("" ::: "memory"); } while (0)
; DI void diff_core(unsigned char* smem, const u16* qptr, const u16* kbase, const u16* vtbase, int vld,
;                   int ntb, int ntw, int nvalid, int ks0, const float* lut, int qpos, bool active, bool grpB,
;                   f32x16 (&O)[4], float& l_out) {
;     ...
;   asm volatile("s_waitcnt vmcnt(0)" :: "v"(qf[0]), "v"(qf[1]), "v"(qf[2]), "v"(qf[3]) : "memory");
;   dma(0, 0); dma(1 < tlast ? 1 : tlast, 1);
;   if (!grpB) { dma(2 < tlast ? 2 : tlast, 2); asm volatile("s_waitcnt vmcnt(8)" ::: "memory"); }
;   else { asm volatile("s_waitcnt vmcnt(4)" ::: "memory"); }
;   D_BAR;
; __device__ void diff_item(const Params& p, unsigned char* smem, bool sample, int b, int h, int qb, float lam) {
;     ...
;   } else {
;     tok = NPROMPT + b * 16 + (r < 16 ? r : 15);
;     qpos = 1024;
;     ntw = 17; ntb = 17; nvalid = 16;
;     active = (g == 0); valid = (r < 16);
;     kbase = p.Kall + ((size_t)NPROMPT + (size_t)b * SKV) * 1024 + h * 128;
;     vtbase = p.VTs + (size_t)(b * 1024 + h * 128) * SKV;
;     vld = SKV;
;   }
;   const u16* qptr = p.Qb + (size_t)tok * 1024 + h * 128 + c * 64 + hh * 8;
.LBB0_525:
	s_andn2_b64 vcc, exec, s[8:9]
	s_cbranch_vccnz .LBB0_403
	v_mov_b32_e32 v201, v160
	s_ashr_i32 s10, s2, 3
	s_and_b32 s59, s2, 7
	v_and_b32_e32 v207, 31, v201
	v_readfirstlane_b32 s67, v201
	s_lshl_b32 s2, s10, 4
	v_cmp_gt_u32_e64 s[8:9], 16, v207
	v_readlane_b32 s36, v255, 0
	s_ashr_i32 s85, s67, 8
	s_add_i32 s2, s2, 0x8000
	v_cndmask_b32_e64 v0, 15, v207, s[8:9]
	s_mul_i32 s11, s10, 0x220000
	v_readlane_b32 s50, v255, 14
	v_add_u32_e32 v0, s2, v0
	s_mul_hi_i32 s2, s10, 0x220000
	v_readlane_b32 s51, v255, 15
	s_add_u32 s11, s50, s11
	s_addc_u32 s12, s51, s2
	s_lshl_b32 s2, s59, 7
	s_lshl_b32 s22, s59, 8
	s_add_u32 s16, s11, s22
	v_readlane_b32 s38, v255, 2
	s_addc_u32 s17, s12, 0
	v_readlane_b32 s39, v255, 3
	s_add_u32 s38, s16, 0x4000000
	s_addc_u32 s39, s17, 0
	s_lshl_b32 s10, s10, 10
	s_or_b32 s10, s2, s10
	s_mul_hi_i32 s11, s10, 0x880
	s_mulk_i32 s10, 0x880
	v_ashrrev_i32_e32 v1, 31, v0
	v_readlane_b32 s48, v255, 12
	v_readlane_b32 s49, v255, 13
	s_add_u32 s60, s70, s10
	v_lshlrev_b64 v[180:181], 11, v[0:1]
	s_addc_u32 s61, s71, s11
	v_lshl_add_u64 v[0:1], s[48:49], 0, v[180:181]
	s_lshl_b32 s10, s85, 6
	v_bfe_u32 v200, v201, 5, 1
	v_lshl_add_u64 v[0:1], v[0:1], 0, s[22:23]
	s_ashr_i32 s11, s10, 31
	v_lshl_add_u64 v[0:1], s[10:11], 1, v[0:1]
	v_lshlrev_b32_e32 v164, 4, v200
	v_lshl_add_u64 v[0:1], v[0:1], 0, v[164:165]
	v_mov_b32_e32 v16, v160
	v_lshlrev_b32_e32 v196, 1, v180
	v_lshl_add_u32 v196, v200, 7, v196
	v_add_u32_e32 v196, s22, v196
	global_load_dword v195, v196, s[80:81]
	global_load_dwordx4 v[128:131], v[0:1], off
	global_load_dwordx4 v[132:135], v[0:1], off offset:32
	global_load_dwordx4 v[136:139], v[0:1], off offset:64
	global_load_dwordx4 v[140:143], v[0:1], off offset:96
	v_readfirstlane_b32 s22, v16
	s_movk_i32 s10, 0xffc0
	s_cmp_eq_u32 s85, 1
	v_mov_b32_e32 v0, s22
	v_bfi_b32 v0, s10, v0, v16
	s_cselect_b64 s[12:13], -1, 0
	s_cmp_lg_u32 s85, 1
	v_ashrrev_i32_e32 v1, 4, v0
	v_lshrrev_b32_e32 v2, 3, v0
	v_lshrrev_b32_e32 v3, 4, v0
	v_add_u32_e32 v0, 0x200, v0
	s_cselect_b64 s[10:11], -1, 0
	s_lshl_b32 s22, s22, 4
	v_xor_b32_e32 v4, v1, v16
	v_lshlrev_b32_e32 v5, 11, v1
	v_xor_b32_e32 v1, v3, v16
	v_ashrrev_i32_e32 v3, 4, v0
	s_and_b32 s22, s22, 0xfffffc00
	v_lshlrev_b32_e32 v4, 4, v4
	v_lshlrev_b32_e32 v1, 3, v1
	v_xor_b32_e32 v6, v3, v16
	s_add_i32 s58, s22, 0
	v_mul_lo_u32 v2, v2, s69
	v_lshrrev_b32_e32 v0, 3, v0
	v_lshlrev_b32_e32 v3, 11, v3
	v_and_b32_e32 v1, 56, v1
	v_lshlrev_b32_e32 v6, 4, v6
	v_and_or_b32 v164, v4, s57, v5
	s_mov_b32 m0, s58
	v_mul_lo_u32 v0, v0, s69
	v_or_b32_e32 v2, v1, v2
	v_and_or_b32 v186, v6, s57, v3
	v_or_b32_e32 v0, v1, v0
	v_lshlrev_b32_e32 v182, 1, v2
	v_lshlrev_b32_e32 v184, 1, v0
	v_mov_b32_e32 v183, v165
	v_mov_b32_e32 v185, v165
	v_lshl_add_u64 v[146:147], s[60:61], 0, v[182:183]
	v_lshl_add_u64 v[144:145], s[60:61], 0, v[184:185]
	v_lshl_add_u64 v[0:1], v[146:147], 0, s[24:25]
	v_lshl_add_u64 v[2:3], v[144:145], 0, s[24:25]
	v_mov_b32_e32 v187, v165
	v_lshl_add_u64 v[190:191], v[146:147], 0, s[18:19]
	v_lshl_add_u64 v[188:189], v[144:145], 0, s[18:19]
	v_readlane_b32 s37, v255, 1
	v_readlane_b32 s40, v255, 4
	v_readlane_b32 s41, v255, 5
	v_readlane_b32 s42, v255, 6
	v_readlane_b32 s43, v255, 7
	s_waitcnt vmcnt(0)
	s_waitcnt vmcnt(0)
	global_load_lds_dwordx4 v164, s[38:39]
	s_add_i32 m0, s58, 0x2000
	v_readlane_b32 s44, v255, 8
	global_load_lds_dwordx4 v186, s[38:39]
	s_add_i32 m0, s58, 0x4000
	v_readlane_b32 s45, v255, 9
	global_load_lds_dwordx4 v182, s[60:61]
	s_add_i32 m0, s58, 0x6000
	v_readlane_b32 s46, v255, 10
	global_load_lds_dwordx4 v184, s[60:61]
	s_add_i32 m0, s58, 0x8000
	s_add_u32 s16, s16, 0x4020000
	s_addc_u32 s17, s17, 0
	global_load_lds_dwordx4 v164, s[16:17]
	s_add_i32 m0, s58, 0xa000
	s_and_b64 vcc, exec, s[12:13]
	global_load_lds_dwordx4 v186, s[16:17]
	s_add_i32 m0, s58, 0xc000
	s_mov_b64 s[16:17], -1
	global_load_lds_dwordx4 v[0:1], off
	s_add_i32 m0, s58, 0xe000
	v_readlane_b32 s47, v255, 11
	global_load_lds_dwordx4 v[2:3], off
	s_cbranch_vccnz .LBB0_528
	s_add_i32 m0, s58, 0x10000
	s_add_u32 s16, s38, 0x40000
	s_addc_u32 s17, s39, 0
	v_lshl_add_u64 v[0:1], s[16:17], 0, v[164:165]
	global_load_lds_dwordx4 v[0:1], off
	v_lshl_add_u64 v[0:1], s[16:17], 0, v[186:187]
	s_add_i32 m0, s58, 0x12000
	s_mov_b64 s[16:17], 0
	global_load_lds_dwordx4 v[0:1], off
	s_add_i32 m0, s58, 0x14000
	s_nop 0
	global_load_lds_dwordx4 v[190:191], off
	s_add_i32 m0, s58, 0x16000
	s_nop 0
	global_load_lds_dwordx4 v[188:189], off
	s_waitcnt vmcnt(8)
